# v56 + per-unit accumulator zero-init with v_pk_mov_b32 (64 instead of 127 moves per wave and unit, 18 sites)
# baseline (speedup 1.0000x reference)
;     __host__ __device__ bool next(int i, Unit& u) const { const int P = (i >> 1) * G + c; if (P >= 256) return false; u.pm = P >> 3; u.pn = (P & 7) + 8 * (i & 1); return true; }
; template <class Epi, class Sched, bool ALIGN_EPI = false, bool SP2 = false>
; __device__ __forceinline__ void gemm_phase(PG8_LAS unsigned char* lds, const Gemm g, const Sched& S, const Epi& E, const int wv) {
;     ...
;         const bool has_next = S.next(ui + 1, nxt);
;         const char* nA = has_next ? (const char*)g.A + (size_t)nxt.pm * tstepA + (g.amod ? (size_t)(nxt.pn % g.amod) * K * 2 : (size_t)0) : cA; const char* nB = has_next ? (const char*)g.Bt + (size_t)nxt.pn * tstepB : cB;
;     ...
; #pragma unroll
;         for (int a = 0; a < 2; ++a)
; #pragma unroll
;             for (int b = 0; b < 2; ++b)
; #pragma unroll
;                 for (int m = 0; m < 4; ++m)
; #pragma unroll
;                     for (int n = 0; n < 2; ++n) acc[a][b][m][n] = (f32x4){0.f, 0.f, 0.f, 0.f};
;         cur = nxt; cA = nA; cB = nB; ++ui;
.LBB0_174:
	s_ashr_i32 s35, s34, 31
	s_lshl_b64 s[46:47], s[34:35], 20
	s_add_u32 s46, s51, s46
	v_mov_b32_e32 v153, 0
	s_addc_u32 s47, s52, s47
	s_andn2_b64 vcc, exec, s[28:29]
	v_mov_b32_e32 v152, v153
	v_pk_mov_b32 v[150:151], v[152:153], v[152:153]
	v_pk_mov_b32 v[148:149], v[152:153], v[152:153]
	v_pk_mov_b32 v[146:147], v[152:153], v[152:153]
	v_pk_mov_b32 v[136:137], v[152:153], v[152:153]
	v_pk_mov_b32 v[134:135], v[152:153], v[152:153]
	v_pk_mov_b32 v[132:133], v[152:153], v[152:153]
	v_pk_mov_b32 v[130:131], v[152:153], v[152:153]
	v_pk_mov_b32 v[120:121], v[152:153], v[152:153]
	v_pk_mov_b32 v[118:119], v[152:153], v[152:153]
	v_pk_mov_b32 v[116:117], v[152:153], v[152:153]
	v_pk_mov_b32 v[114:115], v[152:153], v[152:153]
	v_pk_mov_b32 v[104:105], v[152:153], v[152:153]
	v_pk_mov_b32 v[102:103], v[152:153], v[152:153]
	v_pk_mov_b32 v[100:101], v[152:153], v[152:153]
	v_pk_mov_b32 v[98:99], v[152:153], v[152:153]
	v_pk_mov_b32 v[144:145], v[152:153], v[152:153]
	v_pk_mov_b32 v[142:143], v[152:153], v[152:153]
	v_pk_mov_b32 v[140:141], v[152:153], v[152:153]
	v_pk_mov_b32 v[138:139], v[152:153], v[152:153]
	v_pk_mov_b32 v[128:129], v[152:153], v[152:153]
	v_pk_mov_b32 v[126:127], v[152:153], v[152:153]
	v_pk_mov_b32 v[124:125], v[152:153], v[152:153]
	v_pk_mov_b32 v[122:123], v[152:153], v[152:153]
	v_pk_mov_b32 v[112:113], v[152:153], v[152:153]
	v_pk_mov_b32 v[110:111], v[152:153], v[152:153]
	v_pk_mov_b32 v[108:109], v[152:153], v[152:153]
	v_pk_mov_b32 v[106:107], v[152:153], v[152:153]
	v_pk_mov_b32 v[96:97], v[152:153], v[152:153]
	v_pk_mov_b32 v[94:95], v[152:153], v[152:153]
	v_pk_mov_b32 v[92:93], v[152:153], v[152:153]
	v_pk_mov_b32 v[90:91], v[152:153], v[152:153]
	v_pk_mov_b32 v[80:81], v[152:153], v[152:153]
	v_pk_mov_b32 v[78:79], v[152:153], v[152:153]
	v_pk_mov_b32 v[72:73], v[152:153], v[152:153]
	v_pk_mov_b32 v[70:71], v[152:153], v[152:153]
	v_pk_mov_b32 v[48:49], v[152:153], v[152:153]
	v_pk_mov_b32 v[46:47], v[152:153], v[152:153]
	v_pk_mov_b32 v[44:45], v[152:153], v[152:153]
	v_pk_mov_b32 v[42:43], v[152:153], v[152:153]
	v_pk_mov_b32 v[32:33], v[152:153], v[152:153]
	v_pk_mov_b32 v[30:31], v[152:153], v[152:153]
	v_pk_mov_b32 v[28:29], v[152:153], v[152:153]
	v_pk_mov_b32 v[26:27], v[152:153], v[152:153]
	v_pk_mov_b32 v[16:17], v[152:153], v[152:153]
	v_pk_mov_b32 v[14:15], v[152:153], v[152:153]
	v_pk_mov_b32 v[12:13], v[152:153], v[152:153]
	v_pk_mov_b32 v[10:11], v[152:153], v[152:153]
	v_pk_mov_b32 v[64:65], v[152:153], v[152:153]
	v_pk_mov_b32 v[62:63], v[152:153], v[152:153]
	v_pk_mov_b32 v[56:57], v[152:153], v[152:153]
	v_pk_mov_b32 v[54:55], v[152:153], v[152:153]
	v_pk_mov_b32 v[40:41], v[152:153], v[152:153]
	v_pk_mov_b32 v[38:39], v[152:153], v[152:153]
	v_pk_mov_b32 v[36:37], v[152:153], v[152:153]
	v_pk_mov_b32 v[34:35], v[152:153], v[152:153]
	v_pk_mov_b32 v[24:25], v[152:153], v[152:153]
	v_pk_mov_b32 v[22:23], v[152:153], v[152:153]
	v_pk_mov_b32 v[20:21], v[152:153], v[152:153]
	v_pk_mov_b32 v[18:19], v[152:153], v[152:153]
	v_pk_mov_b32 v[8:9], v[152:153], v[152:153]
	v_pk_mov_b32 v[6:7], v[152:153], v[152:153]
	v_pk_mov_b32 v[4:5], v[152:153], v[152:153]
	v_pk_mov_b32 v[2:3], v[152:153], v[152:153]
	s_cbranch_vccnz .LBB0_178
	s_and_b64 s[42:43], s[42:43], exec
	s_cselect_b32 s11, s47, s13
	s_cselect_b32 s35, s46, s12
	s_add_u32 s12, s12, 0x80080
	s_addc_u32 s13, s13, 0
	s_add_u32 s42, s14, 0x100
	v_mov_b32_e32 v2, 0
	s_addc_u32 s43, s15, 0
	s_mov_b32 s14, 0
	v_mov_b32_e32 v3, v2
	v_pk_mov_b32 v[4:5], v[2:3], v[2:3]
	v_pk_mov_b32 v[6:7], v[2:3], v[2:3]
	v_pk_mov_b32 v[8:9], v[2:3], v[2:3]
	v_pk_mov_b32 v[18:19], v[2:3], v[2:3]
	v_pk_mov_b32 v[20:21], v[2:3], v[2:3]
	v_pk_mov_b32 v[22:23], v[2:3], v[2:3]
	v_pk_mov_b32 v[24:25], v[2:3], v[2:3]
	v_pk_mov_b32 v[34:35], v[2:3], v[2:3]
	v_pk_mov_b32 v[36:37], v[2:3], v[2:3]
	v_pk_mov_b32 v[38:39], v[2:3], v[2:3]
	v_pk_mov_b32 v[40:41], v[2:3], v[2:3]
	v_pk_mov_b32 v[54:55], v[2:3], v[2:3]
	v_pk_mov_b32 v[56:57], v[2:3], v[2:3]
	v_pk_mov_b32 v[62:63], v[2:3], v[2:3]
	v_pk_mov_b32 v[64:65], v[2:3], v[2:3]
	v_pk_mov_b32 v[10:11], v[2:3], v[2:3]
	v_pk_mov_b32 v[12:13], v[2:3], v[2:3]
	v_pk_mov_b32 v[14:15], v[2:3], v[2:3]
	v_pk_mov_b32 v[16:17], v[2:3], v[2:3]
	v_pk_mov_b32 v[26:27], v[2:3], v[2:3]
	v_pk_mov_b32 v[28:29], v[2:3], v[2:3]
	v_pk_mov_b32 v[30:31], v[2:3], v[2:3]
	v_pk_mov_b32 v[32:33], v[2:3], v[2:3]
	v_pk_mov_b32 v[42:43], v[2:3], v[2:3]
	v_pk_mov_b32 v[44:45], v[2:3], v[2:3]
	v_pk_mov_b32 v[46:47], v[2:3], v[2:3]
	v_pk_mov_b32 v[48:49], v[2:3], v[2:3]
	v_pk_mov_b32 v[70:71], v[2:3], v[2:3]
	v_pk_mov_b32 v[72:73], v[2:3], v[2:3]
	v_pk_mov_b32 v[78:79], v[2:3], v[2:3]
	v_pk_mov_b32 v[80:81], v[2:3], v[2:3]
	v_pk_mov_b32 v[90:91], v[2:3], v[2:3]
	v_pk_mov_b32 v[92:93], v[2:3], v[2:3]
	v_pk_mov_b32 v[94:95], v[2:3], v[2:3]
	v_pk_mov_b32 v[96:97], v[2:3], v[2:3]
	v_pk_mov_b32 v[106:107], v[2:3], v[2:3]
	v_pk_mov_b32 v[108:109], v[2:3], v[2:3]
	v_pk_mov_b32 v[110:111], v[2:3], v[2:3]
	v_pk_mov_b32 v[112:113], v[2:3], v[2:3]
	v_pk_mov_b32 v[122:123], v[2:3], v[2:3]
	v_pk_mov_b32 v[124:125], v[2:3], v[2:3]
	v_pk_mov_b32 v[126:127], v[2:3], v[2:3]
	v_pk_mov_b32 v[128:129], v[2:3], v[2:3]
	v_pk_mov_b32 v[138:139], v[2:3], v[2:3]
	v_pk_mov_b32 v[140:141], v[2:3], v[2:3]
	v_pk_mov_b32 v[142:143], v[2:3], v[2:3]
	v_pk_mov_b32 v[144:145], v[2:3], v[2:3]
	v_pk_mov_b32 v[98:99], v[2:3], v[2:3]
	v_pk_mov_b32 v[100:101], v[2:3], v[2:3]
	v_pk_mov_b32 v[102:103], v[2:3], v[2:3]
	v_pk_mov_b32 v[104:105], v[2:3], v[2:3]
	v_pk_mov_b32 v[114:115], v[2:3], v[2:3]
	v_pk_mov_b32 v[116:117], v[2:3], v[2:3]
	v_pk_mov_b32 v[118:119], v[2:3], v[2:3]
	v_pk_mov_b32 v[120:121], v[2:3], v[2:3]
	v_pk_mov_b32 v[130:131], v[2:3], v[2:3]
	v_pk_mov_b32 v[132:133], v[2:3], v[2:3]
	v_pk_mov_b32 v[134:135], v[2:3], v[2:3]
	v_pk_mov_b32 v[136:137], v[2:3], v[2:3]
	v_pk_mov_b32 v[146:147], v[2:3], v[2:3]
	v_pk_mov_b32 v[148:149], v[2:3], v[2:3]
	v_pk_mov_b32 v[150:151], v[2:3], v[2:3]
	v_pk_mov_b32 v[152:153], v[2:3], v[2:3]

; template <class Epi, class Sched, bool ALIGN_EPI = false, bool SP2 = false>
; __device__ __forceinline__ void gemm_phase(PG8_LAS unsigned char* lds, const Gemm g, const Sched& S, const Epi& E, const int wv) {
;     ...
; #pragma unroll
;         for (int a = 0; a < 2; ++a)
; #pragma unroll
;             for (int b = 0; b < 2; ++b)
; #pragma unroll
;                 for (int m = 0; m < 4; ++m)
; #pragma unroll
;                     for (int n = 0; n < 2; ++n) acc[a][b][m][n] = (f32x4){0.f, 0.f, 0.f, 0.f};
;         cur = nxt; cA = nA; cB = nB; ++ui;
.LBB0_334:
	v_mov_b32_e32 v141, 0
	s_andn2_b64 vcc, exec, s[34:35]
	v_mov_b32_e32 v140, v141
	v_pk_mov_b32 v[138:139], v[140:141], v[140:141]
	v_pk_mov_b32 v[144:145], v[140:141], v[140:141]
	v_pk_mov_b32 v[142:143], v[140:141], v[140:141]
	v_pk_mov_b32 v[128:129], v[140:141], v[140:141]
	v_pk_mov_b32 v[126:127], v[140:141], v[140:141]
	v_pk_mov_b32 v[124:125], v[140:141], v[140:141]
	v_pk_mov_b32 v[122:123], v[140:141], v[140:141]
	v_pk_mov_b32 v[112:113], v[140:141], v[140:141]
	v_pk_mov_b32 v[110:111], v[140:141], v[140:141]
	v_pk_mov_b32 v[108:109], v[140:141], v[140:141]
	v_pk_mov_b32 v[106:107], v[140:141], v[140:141]
	v_pk_mov_b32 v[96:97], v[140:141], v[140:141]
	v_pk_mov_b32 v[94:95], v[140:141], v[140:141]
	v_pk_mov_b32 v[92:93], v[140:141], v[140:141]
	v_pk_mov_b32 v[90:91], v[140:141], v[140:141]
	v_pk_mov_b32 v[136:137], v[140:141], v[140:141]
	v_pk_mov_b32 v[134:135], v[140:141], v[140:141]
	v_pk_mov_b32 v[132:133], v[140:141], v[140:141]
	v_pk_mov_b32 v[130:131], v[140:141], v[140:141]
	v_pk_mov_b32 v[120:121], v[140:141], v[140:141]
	v_pk_mov_b32 v[118:119], v[140:141], v[140:141]
	v_pk_mov_b32 v[116:117], v[140:141], v[140:141]
	v_pk_mov_b32 v[114:115], v[140:141], v[140:141]
	v_pk_mov_b32 v[104:105], v[140:141], v[140:141]
	v_pk_mov_b32 v[102:103], v[140:141], v[140:141]
	v_pk_mov_b32 v[100:101], v[140:141], v[140:141]
	v_pk_mov_b32 v[98:99], v[140:141], v[140:141]
	v_pk_mov_b32 v[88:89], v[140:141], v[140:141]
	v_pk_mov_b32 v[86:87], v[140:141], v[140:141]
	v_pk_mov_b32 v[84:85], v[140:141], v[140:141]
	v_pk_mov_b32 v[82:83], v[140:141], v[140:141]
	v_pk_mov_b32 v[80:81], v[140:141], v[140:141]
	v_pk_mov_b32 v[78:79], v[140:141], v[140:141]
	v_pk_mov_b32 v[76:77], v[140:141], v[140:141]
	v_pk_mov_b32 v[74:75], v[140:141], v[140:141]
	v_pk_mov_b32 v[64:65], v[140:141], v[140:141]
	v_pk_mov_b32 v[62:63], v[140:141], v[140:141]
	v_pk_mov_b32 v[60:61], v[140:141], v[140:141]
	v_pk_mov_b32 v[58:59], v[140:141], v[140:141]
	s_nop 0
	v_pk_mov_b32 v[40:41], v[140:141], v[140:141]
	v_pk_mov_b32 v[38:39], v[140:141], v[140:141]
	v_pk_mov_b32 v[36:37], v[140:141], v[140:141]
	v_pk_mov_b32 v[34:35], v[140:141], v[140:141]
	v_pk_mov_b32 v[16:17], v[140:141], v[140:141]
	v_pk_mov_b32 v[14:15], v[140:141], v[140:141]
	v_pk_mov_b32 v[12:13], v[140:141], v[140:141]
	v_pk_mov_b32 v[10:11], v[140:141], v[140:141]
	v_pk_mov_b32 v[72:73], v[140:141], v[140:141]
	v_pk_mov_b32 v[70:71], v[140:141], v[140:141]
	v_pk_mov_b32 v[68:69], v[140:141], v[140:141]
	v_pk_mov_b32 v[66:67], v[140:141], v[140:141]
	v_pk_mov_b32 v[56:57], v[140:141], v[140:141]
	v_pk_mov_b32 v[54:55], v[140:141], v[140:141]
	v_pk_mov_b32 v[52:53], v[140:141], v[140:141]
	v_pk_mov_b32 v[50:51], v[140:141], v[140:141]
	v_pk_mov_b32 v[24:25], v[140:141], v[140:141]
	v_pk_mov_b32 v[22:23], v[140:141], v[140:141]
	v_pk_mov_b32 v[20:21], v[140:141], v[140:141]
	v_pk_mov_b32 v[18:19], v[140:141], v[140:141]
	v_pk_mov_b32 v[8:9], v[140:141], v[140:141]
	v_pk_mov_b32 v[6:7], v[140:141], v[140:141]
	v_pk_mov_b32 v[4:5], v[140:141], v[140:141]
	v_pk_mov_b32 v[2:3], v[140:141], v[140:141]
	s_cbranch_vccnz .LBB0_337
	s_add_u32 s12, s40, 0x80080
	s_addc_u32 s13, s41, 0
	s_add_u32 s11, s14, 0x100
	v_mov_b32_e32 v2, 0
	s_addc_u32 s17, s15, 0
	s_mov_b32 s14, 0
	v_mov_b32_e32 v3, v2
	v_pk_mov_b32 v[4:5], v[2:3], v[2:3]
	v_pk_mov_b32 v[6:7], v[2:3], v[2:3]
	v_pk_mov_b32 v[8:9], v[2:3], v[2:3]
	v_pk_mov_b32 v[18:19], v[2:3], v[2:3]
	v_pk_mov_b32 v[20:21], v[2:3], v[2:3]
	v_pk_mov_b32 v[22:23], v[2:3], v[2:3]
	v_pk_mov_b32 v[24:25], v[2:3], v[2:3]
	v_pk_mov_b32 v[50:51], v[2:3], v[2:3]
	v_pk_mov_b32 v[52:53], v[2:3], v[2:3]
	v_pk_mov_b32 v[54:55], v[2:3], v[2:3]
	v_pk_mov_b32 v[56:57], v[2:3], v[2:3]
	v_pk_mov_b32 v[66:67], v[2:3], v[2:3]
	v_pk_mov_b32 v[68:69], v[2:3], v[2:3]
	v_pk_mov_b32 v[70:71], v[2:3], v[2:3]
	v_pk_mov_b32 v[72:73], v[2:3], v[2:3]
	v_pk_mov_b32 v[10:11], v[2:3], v[2:3]
	v_pk_mov_b32 v[12:13], v[2:3], v[2:3]
	v_pk_mov_b32 v[14:15], v[2:3], v[2:3]
	v_pk_mov_b32 v[16:17], v[2:3], v[2:3]
	v_pk_mov_b32 v[34:35], v[2:3], v[2:3]
	v_pk_mov_b32 v[36:37], v[2:3], v[2:3]
	v_pk_mov_b32 v[38:39], v[2:3], v[2:3]
	v_pk_mov_b32 v[40:41], v[2:3], v[2:3]
	v_pk_mov_b32 v[58:59], v[2:3], v[2:3]
	v_pk_mov_b32 v[60:61], v[2:3], v[2:3]
	v_pk_mov_b32 v[62:63], v[2:3], v[2:3]
	v_pk_mov_b32 v[64:65], v[2:3], v[2:3]
	v_pk_mov_b32 v[74:75], v[2:3], v[2:3]
	v_pk_mov_b32 v[76:77], v[2:3], v[2:3]
	v_pk_mov_b32 v[78:79], v[2:3], v[2:3]
	v_pk_mov_b32 v[80:81], v[2:3], v[2:3]
	v_pk_mov_b32 v[82:83], v[2:3], v[2:3]
	v_pk_mov_b32 v[84:85], v[2:3], v[2:3]
	v_pk_mov_b32 v[86:87], v[2:3], v[2:3]
	v_pk_mov_b32 v[88:89], v[2:3], v[2:3]
	v_pk_mov_b32 v[98:99], v[2:3], v[2:3]
	v_pk_mov_b32 v[100:101], v[2:3], v[2:3]
	v_pk_mov_b32 v[102:103], v[2:3], v[2:3]
	v_pk_mov_b32 v[104:105], v[2:3], v[2:3]
	v_pk_mov_b32 v[114:115], v[2:3], v[2:3]
	v_pk_mov_b32 v[116:117], v[2:3], v[2:3]
	v_pk_mov_b32 v[118:119], v[2:3], v[2:3]
	v_pk_mov_b32 v[120:121], v[2:3], v[2:3]
	v_pk_mov_b32 v[130:131], v[2:3], v[2:3]
	v_pk_mov_b32 v[132:133], v[2:3], v[2:3]
	v_pk_mov_b32 v[134:135], v[2:3], v[2:3]
	v_pk_mov_b32 v[136:137], v[2:3], v[2:3]
	v_pk_mov_b32 v[90:91], v[2:3], v[2:3]
	v_pk_mov_b32 v[92:93], v[2:3], v[2:3]
	v_pk_mov_b32 v[94:95], v[2:3], v[2:3]
	v_pk_mov_b32 v[96:97], v[2:3], v[2:3]
	v_pk_mov_b32 v[106:107], v[2:3], v[2:3]
	v_pk_mov_b32 v[108:109], v[2:3], v[2:3]
	v_pk_mov_b32 v[110:111], v[2:3], v[2:3]
	v_pk_mov_b32 v[112:113], v[2:3], v[2:3]
	v_pk_mov_b32 v[122:123], v[2:3], v[2:3]
	v_pk_mov_b32 v[124:125], v[2:3], v[2:3]
	v_pk_mov_b32 v[126:127], v[2:3], v[2:3]
	v_pk_mov_b32 v[128:129], v[2:3], v[2:3]
	v_pk_mov_b32 v[142:143], v[2:3], v[2:3]
	v_pk_mov_b32 v[144:145], v[2:3], v[2:3]
	v_pk_mov_b32 v[138:139], v[2:3], v[2:3]
	v_pk_mov_b32 v[140:141], v[2:3], v[2:3]

; template <class Epi, class Sched, bool ALIGN_EPI = false, bool SP2 = false>
; __device__ __forceinline__ void gemm_phase(PG8_LAS unsigned char* lds, const Gemm g, const Sched& S, const Epi& E, const int wv) {
;     ...
; #pragma unroll
;         for (int a = 0; a < 2; ++a)
; #pragma unroll
;             for (int b = 0; b < 2; ++b)
; #pragma unroll
;                 for (int m = 0; m < 4; ++m)
; #pragma unroll
;                     for (int n = 0; n < 2; ++n) acc[a][b][m][n] = (f32x4){0.f, 0.f, 0.f, 0.f};
;         cur = nxt; cA = nA; cB = nB; ++ui;
.LBB0_671:
	s_ashr_i32 s89, s88, 31
	s_lshl_b64 s[14:15], s[88:89], 20
	s_add_u32 s14, s17, s14
	v_mov_b32_e32 v137, 0
	s_addc_u32 s15, s19, s15
	s_andn2_b64 vcc, exec, s[10:11]
	v_mov_b32_e32 v136, v137
	v_pk_mov_b32 v[134:135], v[136:137], v[136:137]
	v_pk_mov_b32 v[132:133], v[136:137], v[136:137]
	v_pk_mov_b32 v[130:131], v[136:137], v[136:137]
	v_pk_mov_b32 v[112:113], v[136:137], v[136:137]
	v_pk_mov_b32 v[110:111], v[136:137], v[136:137]
	v_pk_mov_b32 v[108:109], v[136:137], v[136:137]
	v_pk_mov_b32 v[106:107], v[136:137], v[136:137]
	v_pk_mov_b32 v[96:97], v[136:137], v[136:137]
	v_pk_mov_b32 v[94:95], v[136:137], v[136:137]
	v_pk_mov_b32 v[92:93], v[136:137], v[136:137]
	v_pk_mov_b32 v[90:91], v[136:137], v[136:137]
	v_pk_mov_b32 v[80:81], v[136:137], v[136:137]
	v_pk_mov_b32 v[78:79], v[136:137], v[136:137]
	v_pk_mov_b32 v[76:77], v[136:137], v[136:137]
	v_pk_mov_b32 v[74:75], v[136:137], v[136:137]
	v_pk_mov_b32 v[124:125], v[136:137], v[136:137]
	v_pk_mov_b32 v[122:123], v[136:137], v[136:137]
	v_pk_mov_b32 v[120:121], v[136:137], v[136:137]
	v_pk_mov_b32 v[118:119], v[136:137], v[136:137]
	v_pk_mov_b32 v[104:105], v[136:137], v[136:137]
	v_pk_mov_b32 v[102:103], v[136:137], v[136:137]
	v_pk_mov_b32 v[100:101], v[136:137], v[136:137]
	v_pk_mov_b32 v[98:99], v[136:137], v[136:137]
	v_pk_mov_b32 v[88:89], v[136:137], v[136:137]
	v_pk_mov_b32 v[86:87], v[136:137], v[136:137]
	v_pk_mov_b32 v[84:85], v[136:137], v[136:137]
	v_pk_mov_b32 v[82:83], v[136:137], v[136:137]
	v_pk_mov_b32 v[72:73], v[136:137], v[136:137]
	v_pk_mov_b32 v[70:71], v[136:137], v[136:137]
	v_pk_mov_b32 v[68:69], v[136:137], v[136:137]
	v_pk_mov_b32 v[66:67], v[136:137], v[136:137]
	v_pk_mov_b32 v[64:65], v[136:137], v[136:137]
	v_pk_mov_b32 v[62:63], v[136:137], v[136:137]
	v_pk_mov_b32 v[60:61], v[136:137], v[136:137]
	v_pk_mov_b32 v[58:59], v[136:137], v[136:137]
	s_nop 0
	v_pk_mov_b32 v[48:49], v[136:137], v[136:137]
	v_pk_mov_b32 v[46:47], v[136:137], v[136:137]
	v_pk_mov_b32 v[44:45], v[136:137], v[136:137]
	v_pk_mov_b32 v[42:43], v[136:137], v[136:137]
	v_pk_mov_b32 v[32:33], v[136:137], v[136:137]
	v_pk_mov_b32 v[30:31], v[136:137], v[136:137]
	v_pk_mov_b32 v[28:29], v[136:137], v[136:137]
	v_pk_mov_b32 v[26:27], v[136:137], v[136:137]
	v_pk_mov_b32 v[16:17], v[136:137], v[136:137]
	v_pk_mov_b32 v[14:15], v[136:137], v[136:137]
	v_pk_mov_b32 v[12:13], v[136:137], v[136:137]
	v_pk_mov_b32 v[10:11], v[136:137], v[136:137]
	v_pk_mov_b32 v[56:57], v[136:137], v[136:137]
	v_pk_mov_b32 v[54:55], v[136:137], v[136:137]
	v_pk_mov_b32 v[52:53], v[136:137], v[136:137]
	v_pk_mov_b32 v[50:51], v[136:137], v[136:137]
	v_pk_mov_b32 v[40:41], v[136:137], v[136:137]
	v_pk_mov_b32 v[38:39], v[136:137], v[136:137]
	v_pk_mov_b32 v[36:37], v[136:137], v[136:137]
	v_pk_mov_b32 v[34:35], v[136:137], v[136:137]
	v_pk_mov_b32 v[24:25], v[136:137], v[136:137]
	v_pk_mov_b32 v[22:23], v[136:137], v[136:137]
	v_pk_mov_b32 v[20:21], v[136:137], v[136:137]
	v_pk_mov_b32 v[18:19], v[136:137], v[136:137]
	v_pk_mov_b32 v[8:9], v[136:137], v[136:137]
	v_pk_mov_b32 v[6:7], v[136:137], v[136:137]
	v_pk_mov_b32 v[4:5], v[136:137], v[136:137]
	v_pk_mov_b32 v[2:3], v[136:137], v[136:137]
	s_cbranch_vccz .LBB0_698
	s_and_b64 vcc, exec, s[48:49]
	s_cbranch_vccnz .LBB0_701

;     __host__ __device__ bool next(int i, Unit& u) const { const int P = (i >> 1) * G + c; if (P >= 256) return false; u.pm = P >> 3; u.pn = (P & 7) + 8 * (i & 1); return true; }
; template <class Epi, class Sched, bool ALIGN_EPI = false, bool SP2 = false>
; __device__ __forceinline__ void gemm_phase(PG8_LAS unsigned char* lds, const Gemm g, const Sched& S, const Epi& E, const int wv) {
;     ...
;         const bool has_next = S.next(ui + 1, nxt);
;         const char* nA = has_next ? (const char*)g.A + (size_t)nxt.pm * tstepA + (g.amod ? (size_t)(nxt.pn % g.amod) * K * 2 : (size_t)0) : cA; const char* nB = has_next ? (const char*)g.Bt + (size_t)nxt.pn * tstepB : cB;
;         for (int t = 0; t < nt; t += 2) {
;             const bool last = (t == nt - 2);
;             const char* a1 = cA + (size_t)(t + 1) * kstep;
;             const char* a2 = last ? nA : cA + (size_t)(t + 2) * kstep; const char* b2 = last ? nB : cB + (size_t)(t + 2) * kstep;
;             const char* a3 = a2 + kstep; const char* b3 = b2 + kstep;
;     ...
; #pragma unroll
;         for (int a = 0; a < 2; ++a)
; #pragma unroll
;             for (int b = 0; b < 2; ++b)
; #pragma unroll
;                 for (int m = 0; m < 4; ++m)
; #pragma unroll
;                     for (int n = 0; n < 2; ++n) acc[a][b][m][n] = (f32x4){0.f, 0.f, 0.f, 0.f};
;         cur = nxt; cA = nA; cB = nB; ++ui;
.LBB0_698:
	s_and_b64 s[44:45], s[44:45], exec
	s_cselect_b32 s31, s15, s55
	s_cselect_b32 s71, s14, s54
	s_add_u32 s44, s54, 0x80080
	s_addc_u32 s45, s55, 0
	s_add_u32 s56, s56, 0x100
	v_mov_b32_e32 v2, 0
	s_addc_u32 s57, s57, 0
	s_mov_b32 s54, 0
	v_mov_b32_e32 v3, v2
	v_pk_mov_b32 v[4:5], v[2:3], v[2:3]
	v_pk_mov_b32 v[6:7], v[2:3], v[2:3]
	v_pk_mov_b32 v[8:9], v[2:3], v[2:3]
	v_pk_mov_b32 v[18:19], v[2:3], v[2:3]
	v_pk_mov_b32 v[20:21], v[2:3], v[2:3]
	v_pk_mov_b32 v[22:23], v[2:3], v[2:3]
	v_pk_mov_b32 v[24:25], v[2:3], v[2:3]
	v_pk_mov_b32 v[34:35], v[2:3], v[2:3]
	v_pk_mov_b32 v[36:37], v[2:3], v[2:3]
	v_pk_mov_b32 v[38:39], v[2:3], v[2:3]
	v_pk_mov_b32 v[40:41], v[2:3], v[2:3]
	v_pk_mov_b32 v[50:51], v[2:3], v[2:3]
	v_pk_mov_b32 v[52:53], v[2:3], v[2:3]
	v_pk_mov_b32 v[54:55], v[2:3], v[2:3]
	v_pk_mov_b32 v[56:57], v[2:3], v[2:3]
	v_pk_mov_b32 v[10:11], v[2:3], v[2:3]
	v_pk_mov_b32 v[12:13], v[2:3], v[2:3]
	v_pk_mov_b32 v[14:15], v[2:3], v[2:3]
	v_pk_mov_b32 v[16:17], v[2:3], v[2:3]
	v_pk_mov_b32 v[26:27], v[2:3], v[2:3]
	v_pk_mov_b32 v[28:29], v[2:3], v[2:3]
	v_pk_mov_b32 v[30:31], v[2:3], v[2:3]
	v_pk_mov_b32 v[32:33], v[2:3], v[2:3]
	v_pk_mov_b32 v[42:43], v[2:3], v[2:3]
	v_pk_mov_b32 v[44:45], v[2:3], v[2:3]
	v_pk_mov_b32 v[46:47], v[2:3], v[2:3]
	v_pk_mov_b32 v[48:49], v[2:3], v[2:3]
	v_pk_mov_b32 v[58:59], v[2:3], v[2:3]
	v_pk_mov_b32 v[60:61], v[2:3], v[2:3]
	v_pk_mov_b32 v[62:63], v[2:3], v[2:3]
	v_pk_mov_b32 v[64:65], v[2:3], v[2:3]
	v_pk_mov_b32 v[66:67], v[2:3], v[2:3]
	v_pk_mov_b32 v[68:69], v[2:3], v[2:3]
	v_pk_mov_b32 v[70:71], v[2:3], v[2:3]
	v_pk_mov_b32 v[72:73], v[2:3], v[2:3]
	v_pk_mov_b32 v[82:83], v[2:3], v[2:3]
	v_pk_mov_b32 v[84:85], v[2:3], v[2:3]
	v_pk_mov_b32 v[86:87], v[2:3], v[2:3]
	v_pk_mov_b32 v[88:89], v[2:3], v[2:3]
	v_pk_mov_b32 v[98:99], v[2:3], v[2:3]
	v_pk_mov_b32 v[100:101], v[2:3], v[2:3]
	v_pk_mov_b32 v[102:103], v[2:3], v[2:3]
	v_pk_mov_b32 v[104:105], v[2:3], v[2:3]
	v_pk_mov_b32 v[118:119], v[2:3], v[2:3]
	v_pk_mov_b32 v[120:121], v[2:3], v[2:3]
	v_pk_mov_b32 v[122:123], v[2:3], v[2:3]
	v_pk_mov_b32 v[124:125], v[2:3], v[2:3]
	v_pk_mov_b32 v[74:75], v[2:3], v[2:3]
	v_pk_mov_b32 v[76:77], v[2:3], v[2:3]
	v_pk_mov_b32 v[78:79], v[2:3], v[2:3]
	v_pk_mov_b32 v[80:81], v[2:3], v[2:3]
	v_pk_mov_b32 v[90:91], v[2:3], v[2:3]
	v_pk_mov_b32 v[92:93], v[2:3], v[2:3]
	v_pk_mov_b32 v[94:95], v[2:3], v[2:3]
	v_pk_mov_b32 v[96:97], v[2:3], v[2:3]
	v_pk_mov_b32 v[106:107], v[2:3], v[2:3]
	v_pk_mov_b32 v[108:109], v[2:3], v[2:3]
	v_pk_mov_b32 v[110:111], v[2:3], v[2:3]
	v_pk_mov_b32 v[112:113], v[2:3], v[2:3]
	v_pk_mov_b32 v[130:131], v[2:3], v[2:3]
	v_pk_mov_b32 v[132:133], v[2:3], v[2:3]
	v_pk_mov_b32 v[134:135], v[2:3], v[2:3]
	v_pk_mov_b32 v[136:137], v[2:3], v[2:3]

; template <class Epi, class Sched, bool ALIGN_EPI = false, bool SP2 = false>
; __device__ __forceinline__ void gemm_phase(PG8_LAS unsigned char* lds, const Gemm g, const Sched& S, const Epi& E, const int wv) {
;     ...
; #pragma unroll
;         for (int a = 0; a < 2; ++a)
; #pragma unroll
;             for (int b = 0; b < 2; ++b)
; #pragma unroll
;                 for (int m = 0; m < 4; ++m)
; #pragma unroll
;                     for (int n = 0; n < 2; ++n) acc[a][b][m][n] = (f32x4){0.f, 0.f, 0.f, 0.f};
;         cur = nxt; cA = nA; cB = nB; ++ui;
.LBB0_782:
	s_ashr_i32 s51, s50, 31
	s_lshl_b64 s[14:15], s[50:51], 20
	s_add_u32 s90, s59, s14
	v_mov_b32_e32 v121, 0
	s_addc_u32 s91, s60, s15
	s_andn2_b64 vcc, exec, s[28:29]
	v_mov_b32_e32 v120, v121
	v_pk_mov_b32 v[118:119], v[120:121], v[120:121]
	v_pk_mov_b32 v[48:49], v[120:121], v[120:121]
	v_pk_mov_b32 v[46:47], v[120:121], v[120:121]
	v_pk_mov_b32 v[112:113], v[120:121], v[120:121]
	v_pk_mov_b32 v[110:111], v[120:121], v[120:121]
	v_pk_mov_b32 v[40:41], v[120:121], v[120:121]
	v_pk_mov_b32 v[38:39], v[120:121], v[120:121]
	v_pk_mov_b32 v[136:137], v[120:121], v[120:121]
	v_pk_mov_b32 v[134:135], v[120:121], v[120:121]
	v_pk_mov_b32 v[64:65], v[120:121], v[120:121]
	v_pk_mov_b32 v[62:63], v[120:121], v[120:121]
	v_pk_mov_b32 v[132:133], v[120:121], v[120:121]
	v_pk_mov_b32 v[130:131], v[120:121], v[120:121]
	v_pk_mov_b32 v[60:61], v[120:121], v[120:121]
	v_pk_mov_b32 v[58:59], v[120:121], v[120:121]
	v_pk_mov_b32 v[116:117], v[120:121], v[120:121]
	v_pk_mov_b32 v[114:115], v[120:121], v[120:121]
	v_pk_mov_b32 v[44:45], v[120:121], v[120:121]
	v_pk_mov_b32 v[42:43], v[120:121], v[120:121]
	v_pk_mov_b32 v[108:109], v[120:121], v[120:121]
	v_pk_mov_b32 v[106:107], v[120:121], v[120:121]
	v_pk_mov_b32 v[36:37], v[120:121], v[120:121]
	v_pk_mov_b32 v[34:35], v[120:121], v[120:121]
	v_pk_mov_b32 v[128:129], v[120:121], v[120:121]
	v_pk_mov_b32 v[126:127], v[120:121], v[120:121]
	v_pk_mov_b32 v[56:57], v[120:121], v[120:121]
	v_pk_mov_b32 v[54:55], v[120:121], v[120:121]
	v_pk_mov_b32 v[124:125], v[120:121], v[120:121]
	v_pk_mov_b32 v[122:123], v[120:121], v[120:121]
	v_pk_mov_b32 v[52:53], v[120:121], v[120:121]
	v_pk_mov_b32 v[50:51], v[120:121], v[120:121]
	v_pk_mov_b32 v[88:89], v[120:121], v[120:121]
	v_pk_mov_b32 v[86:87], v[120:121], v[120:121]
	v_pk_mov_b32 v[16:17], v[120:121], v[120:121]
	v_pk_mov_b32 v[14:15], v[120:121], v[120:121]
	v_pk_mov_b32 v[72:73], v[120:121], v[120:121]
	v_pk_mov_b32 v[70:71], v[120:121], v[120:121]
	v_pk_mov_b32 v[8:9], v[120:121], v[120:121]
	v_pk_mov_b32 v[6:7], v[120:121], v[120:121]
	v_pk_mov_b32 v[104:105], v[120:121], v[120:121]
	v_pk_mov_b32 v[102:103], v[120:121], v[120:121]
	v_pk_mov_b32 v[32:33], v[120:121], v[120:121]
	v_pk_mov_b32 v[30:31], v[120:121], v[120:121]
	v_pk_mov_b32 v[100:101], v[120:121], v[120:121]
	v_pk_mov_b32 v[98:99], v[120:121], v[120:121]
	v_pk_mov_b32 v[28:29], v[120:121], v[120:121]
	v_pk_mov_b32 v[26:27], v[120:121], v[120:121]
	v_pk_mov_b32 v[84:85], v[120:121], v[120:121]
	v_pk_mov_b32 v[82:83], v[120:121], v[120:121]
	v_pk_mov_b32 v[12:13], v[120:121], v[120:121]
	v_pk_mov_b32 v[10:11], v[120:121], v[120:121]
	v_pk_mov_b32 v[68:69], v[120:121], v[120:121]
	v_pk_mov_b32 v[66:67], v[120:121], v[120:121]
	v_pk_mov_b32 v[4:5], v[120:121], v[120:121]
	v_pk_mov_b32 v[2:3], v[120:121], v[120:121]
	v_pk_mov_b32 v[96:97], v[120:121], v[120:121]
	v_pk_mov_b32 v[94:95], v[120:121], v[120:121]
	v_pk_mov_b32 v[24:25], v[120:121], v[120:121]
	v_pk_mov_b32 v[22:23], v[120:121], v[120:121]
	v_pk_mov_b32 v[92:93], v[120:121], v[120:121]
	v_pk_mov_b32 v[90:91], v[120:121], v[120:121]
	v_pk_mov_b32 v[20:21], v[120:121], v[120:121]
	v_pk_mov_b32 v[18:19], v[120:121], v[120:121]
	s_cbranch_vccz .LBB0_808
	s_and_b64 vcc, exec, s[30:31]
	s_cbranch_vccnz .LBB0_811

;     __host__ __device__ bool next(int i, Unit& u) const { const int P = (i >> 1) * G + c; if (P >= 256) return false; u.pm = P >> 3; u.pn = (P & 7) + 8 * (i & 1); return true; }
; template <class Epi, class Sched, bool ALIGN_EPI = false, bool SP2 = false>
; __device__ __forceinline__ void gemm_phase(PG8_LAS unsigned char* lds, const Gemm g, const Sched& S, const Epi& E, const int wv) {
;     ...
;         const bool has_next = S.next(ui + 1, nxt);
;         const char* nA = has_next ? (const char*)g.A + (size_t)nxt.pm * tstepA + (g.amod ? (size_t)(nxt.pn % g.amod) * K * 2 : (size_t)0) : cA; const char* nB = has_next ? (const char*)g.Bt + (size_t)nxt.pn * tstepB : cB;
;         for (int t = 0; t < nt; t += 2) {
;             const bool last = (t == nt - 2);
;             const char* a1 = cA + (size_t)(t + 1) * kstep;
;             const char* a2 = last ? nA : cA + (size_t)(t + 2) * kstep; const char* b2 = last ? nB : cB + (size_t)(t + 2) * kstep;
;             const char* a3 = a2 + kstep; const char* b3 = b2 + kstep;
;     ...
; #pragma unroll
;         for (int a = 0; a < 2; ++a)
; #pragma unroll
;             for (int b = 0; b < 2; ++b)
; #pragma unroll
;                 for (int m = 0; m < 4; ++m)
; #pragma unroll
;                     for (int n = 0; n < 2; ++n) acc[a][b][m][n] = (f32x4){0.f, 0.f, 0.f, 0.f};
;         cur = nxt; cA = nA; cB = nB; ++ui;
.LBB0_808:
	s_and_b64 s[14:15], s[46:47], exec
	s_cselect_b32 s11, s91, s49
	s_cselect_b32 s13, s90, s48
	s_add_u32 s35, s52, 0x100
	v_mov_b32_e32 v18, 0
	s_addc_u32 s51, s53, 0
	s_mov_b32 s46, 0
	v_mov_b32_e32 v19, v18
	v_pk_mov_b32 v[20:21], v[18:19], v[18:19]
	v_pk_mov_b32 v[90:91], v[18:19], v[18:19]
	v_pk_mov_b32 v[92:93], v[18:19], v[18:19]
	v_pk_mov_b32 v[22:23], v[18:19], v[18:19]
	v_pk_mov_b32 v[24:25], v[18:19], v[18:19]
	v_pk_mov_b32 v[94:95], v[18:19], v[18:19]
	v_pk_mov_b32 v[96:97], v[18:19], v[18:19]
	v_pk_mov_b32 v[2:3], v[18:19], v[18:19]
	v_pk_mov_b32 v[4:5], v[18:19], v[18:19]
	v_pk_mov_b32 v[66:67], v[18:19], v[18:19]
	v_pk_mov_b32 v[68:69], v[18:19], v[18:19]
	v_pk_mov_b32 v[10:11], v[18:19], v[18:19]
	v_pk_mov_b32 v[12:13], v[18:19], v[18:19]
	v_pk_mov_b32 v[82:83], v[18:19], v[18:19]
	v_pk_mov_b32 v[84:85], v[18:19], v[18:19]
	v_pk_mov_b32 v[26:27], v[18:19], v[18:19]
	v_pk_mov_b32 v[28:29], v[18:19], v[18:19]
	v_pk_mov_b32 v[98:99], v[18:19], v[18:19]
	v_pk_mov_b32 v[100:101], v[18:19], v[18:19]
	v_pk_mov_b32 v[30:31], v[18:19], v[18:19]
	v_pk_mov_b32 v[32:33], v[18:19], v[18:19]
	v_pk_mov_b32 v[102:103], v[18:19], v[18:19]
	v_pk_mov_b32 v[104:105], v[18:19], v[18:19]
	v_pk_mov_b32 v[6:7], v[18:19], v[18:19]
	v_pk_mov_b32 v[8:9], v[18:19], v[18:19]
	v_pk_mov_b32 v[70:71], v[18:19], v[18:19]
	v_pk_mov_b32 v[72:73], v[18:19], v[18:19]
	v_pk_mov_b32 v[14:15], v[18:19], v[18:19]
	v_pk_mov_b32 v[16:17], v[18:19], v[18:19]
	v_pk_mov_b32 v[86:87], v[18:19], v[18:19]
	v_pk_mov_b32 v[88:89], v[18:19], v[18:19]
	v_pk_mov_b32 v[50:51], v[18:19], v[18:19]
	v_pk_mov_b32 v[52:53], v[18:19], v[18:19]
	v_pk_mov_b32 v[122:123], v[18:19], v[18:19]
	v_pk_mov_b32 v[124:125], v[18:19], v[18:19]
	v_pk_mov_b32 v[54:55], v[18:19], v[18:19]
	v_pk_mov_b32 v[56:57], v[18:19], v[18:19]
	v_pk_mov_b32 v[126:127], v[18:19], v[18:19]
	v_pk_mov_b32 v[128:129], v[18:19], v[18:19]
	v_pk_mov_b32 v[34:35], v[18:19], v[18:19]
	v_pk_mov_b32 v[36:37], v[18:19], v[18:19]
	v_pk_mov_b32 v[106:107], v[18:19], v[18:19]
	v_pk_mov_b32 v[108:109], v[18:19], v[18:19]
	v_pk_mov_b32 v[42:43], v[18:19], v[18:19]
	v_pk_mov_b32 v[44:45], v[18:19], v[18:19]
	v_pk_mov_b32 v[114:115], v[18:19], v[18:19]
	v_pk_mov_b32 v[116:117], v[18:19], v[18:19]
	v_pk_mov_b32 v[58:59], v[18:19], v[18:19]
	v_pk_mov_b32 v[60:61], v[18:19], v[18:19]
	v_pk_mov_b32 v[130:131], v[18:19], v[18:19]
	v_pk_mov_b32 v[132:133], v[18:19], v[18:19]
	v_pk_mov_b32 v[62:63], v[18:19], v[18:19]
	v_pk_mov_b32 v[64:65], v[18:19], v[18:19]
	v_pk_mov_b32 v[134:135], v[18:19], v[18:19]
	v_pk_mov_b32 v[136:137], v[18:19], v[18:19]
	v_pk_mov_b32 v[38:39], v[18:19], v[18:19]
	v_pk_mov_b32 v[40:41], v[18:19], v[18:19]
	v_pk_mov_b32 v[110:111], v[18:19], v[18:19]
	v_pk_mov_b32 v[112:113], v[18:19], v[18:19]
	v_pk_mov_b32 v[46:47], v[18:19], v[18:19]
	v_pk_mov_b32 v[48:49], v[18:19], v[18:19]
	v_pk_mov_b32 v[118:119], v[18:19], v[18:19]
	v_pk_mov_b32 v[120:121], v[18:19], v[18:19]

; template <class Epi, class Sched, bool ALIGN_EPI = false, bool SP2 = false>
; __device__ __forceinline__ void gemm_phase(PG8_LAS unsigned char* lds, const Gemm g, const Sched& S, const Epi& E, const int wv) {
;     ...
; #pragma unroll
;         for (int a = 0; a < 2; ++a)
; #pragma unroll
;             for (int b = 0; b < 2; ++b)
; #pragma unroll
;                 for (int m = 0; m < 4; ++m)
; #pragma unroll
;                     for (int n = 0; n < 2; ++n) acc[a][b][m][n] = (f32x4){0.f, 0.f, 0.f, 0.f};
;         cur = nxt; cA = nA; cB = nB; ++ui;
.LBB0_964:
	v_mov_b32_e32 v137, 0
	s_andn2_b64 vcc, exec, s[10:11]
	v_mov_b32_e32 v136, v137
	v_pk_mov_b32 v[134:135], v[136:137], v[136:137]
	v_pk_mov_b32 v[132:133], v[136:137], v[136:137]
	v_pk_mov_b32 v[130:131], v[136:137], v[136:137]
	v_pk_mov_b32 v[112:113], v[136:137], v[136:137]
	v_pk_mov_b32 v[110:111], v[136:137], v[136:137]
	v_pk_mov_b32 v[108:109], v[136:137], v[136:137]
	v_pk_mov_b32 v[106:107], v[136:137], v[136:137]
	v_pk_mov_b32 v[96:97], v[136:137], v[136:137]
	v_pk_mov_b32 v[94:95], v[136:137], v[136:137]
	v_pk_mov_b32 v[92:93], v[136:137], v[136:137]
	v_pk_mov_b32 v[90:91], v[136:137], v[136:137]
	v_pk_mov_b32 v[80:81], v[136:137], v[136:137]
	v_pk_mov_b32 v[78:79], v[136:137], v[136:137]
	v_pk_mov_b32 v[76:77], v[136:137], v[136:137]
	v_pk_mov_b32 v[74:75], v[136:137], v[136:137]
	v_pk_mov_b32 v[124:125], v[136:137], v[136:137]
	v_pk_mov_b32 v[122:123], v[136:137], v[136:137]
	v_pk_mov_b32 v[120:121], v[136:137], v[136:137]
	v_pk_mov_b32 v[118:119], v[136:137], v[136:137]
	v_pk_mov_b32 v[104:105], v[136:137], v[136:137]
	v_pk_mov_b32 v[102:103], v[136:137], v[136:137]
	v_pk_mov_b32 v[100:101], v[136:137], v[136:137]
	v_pk_mov_b32 v[98:99], v[136:137], v[136:137]
	v_pk_mov_b32 v[88:89], v[136:137], v[136:137]
	v_pk_mov_b32 v[86:87], v[136:137], v[136:137]
	v_pk_mov_b32 v[84:85], v[136:137], v[136:137]
	v_pk_mov_b32 v[82:83], v[136:137], v[136:137]
	v_pk_mov_b32 v[72:73], v[136:137], v[136:137]
	v_pk_mov_b32 v[70:71], v[136:137], v[136:137]
	v_pk_mov_b32 v[68:69], v[136:137], v[136:137]
	v_pk_mov_b32 v[66:67], v[136:137], v[136:137]
	v_pk_mov_b32 v[64:65], v[136:137], v[136:137]
	v_pk_mov_b32 v[62:63], v[136:137], v[136:137]
	v_pk_mov_b32 v[60:61], v[136:137], v[136:137]
	v_pk_mov_b32 v[58:59], v[136:137], v[136:137]
	v_pk_mov_b32 v[48:49], v[136:137], v[136:137]
	v_pk_mov_b32 v[46:47], v[136:137], v[136:137]
	v_pk_mov_b32 v[44:45], v[136:137], v[136:137]
	v_pk_mov_b32 v[42:43], v[136:137], v[136:137]
	v_pk_mov_b32 v[32:33], v[136:137], v[136:137]
	v_pk_mov_b32 v[30:31], v[136:137], v[136:137]
	v_pk_mov_b32 v[28:29], v[136:137], v[136:137]
	v_pk_mov_b32 v[26:27], v[136:137], v[136:137]
	v_pk_mov_b32 v[16:17], v[136:137], v[136:137]
	v_pk_mov_b32 v[14:15], v[136:137], v[136:137]
	v_pk_mov_b32 v[12:13], v[136:137], v[136:137]
	v_pk_mov_b32 v[10:11], v[136:137], v[136:137]
	v_pk_mov_b32 v[56:57], v[136:137], v[136:137]
	v_pk_mov_b32 v[54:55], v[136:137], v[136:137]
	v_pk_mov_b32 v[52:53], v[136:137], v[136:137]
	v_pk_mov_b32 v[50:51], v[136:137], v[136:137]
	v_pk_mov_b32 v[40:41], v[136:137], v[136:137]
	v_pk_mov_b32 v[38:39], v[136:137], v[136:137]
	v_pk_mov_b32 v[36:37], v[136:137], v[136:137]
	v_pk_mov_b32 v[34:35], v[136:137], v[136:137]
	v_pk_mov_b32 v[24:25], v[136:137], v[136:137]
	v_pk_mov_b32 v[22:23], v[136:137], v[136:137]
	v_pk_mov_b32 v[20:21], v[136:137], v[136:137]
	v_pk_mov_b32 v[18:19], v[136:137], v[136:137]
	v_pk_mov_b32 v[8:9], v[136:137], v[136:137]
	v_pk_mov_b32 v[6:7], v[136:137], v[136:137]
	v_pk_mov_b32 v[4:5], v[136:137], v[136:137]
	v_pk_mov_b32 v[2:3], v[136:137], v[136:137]
	s_cbranch_vccz .LBB0_989
	s_and_b64 vcc, exec, s[28:29]
	s_cbranch_vccnz .LBB0_992

;     __host__ __device__ bool next(int i, Unit& u) const { const int P = (i >> 1) * G + c; if (P >= 256) return false; u.pm = P >> 3; u.pn = (P & 7) + 8 * (i & 1); return true; }
; template <class Epi, class Sched, bool ALIGN_EPI = false, bool SP2 = false>
; __device__ __forceinline__ void gemm_phase(PG8_LAS unsigned char* lds, const Gemm g, const Sched& S, const Epi& E, const int wv) {
;     ...
;         const bool has_next = S.next(ui + 1, nxt);
;         const char* nA = has_next ? (const char*)g.A + (size_t)nxt.pm * tstepA + (g.amod ? (size_t)(nxt.pn % g.amod) * K * 2 : (size_t)0) : cA; const char* nB = has_next ? (const char*)g.Bt + (size_t)nxt.pn * tstepB : cB;
;         for (int t = 0; t < nt; t += 2) {
;             const bool last = (t == nt - 2);
;             const char* a1 = cA + (size_t)(t + 1) * kstep;
;             const char* a2 = last ? nA : cA + (size_t)(t + 2) * kstep; const char* b2 = last ? nB : cB + (size_t)(t + 2) * kstep;
;             const char* a3 = a2 + kstep; const char* b3 = b2 + kstep;
;     ...
; #pragma unroll
;         for (int a = 0; a < 2; ++a)
; #pragma unroll
;             for (int b = 0; b < 2; ++b)
; #pragma unroll
;                 for (int m = 0; m < 4; ++m)
; #pragma unroll
;                     for (int n = 0; n < 2; ++n) acc[a][b][m][n] = (f32x4){0.f, 0.f, 0.f, 0.f};
;         cur = nxt; cA = nA; cB = nB; ++ui;
.LBB0_989:
	s_add_u32 s65, s34, 0x100
	v_mov_b32_e32 v2, 0
	s_addc_u32 s66, s35, 0
	s_mov_b32 s44, 0
	v_mov_b32_e32 v3, v2
	v_pk_mov_b32 v[4:5], v[2:3], v[2:3]
	v_pk_mov_b32 v[6:7], v[2:3], v[2:3]
	v_pk_mov_b32 v[8:9], v[2:3], v[2:3]
	v_pk_mov_b32 v[18:19], v[2:3], v[2:3]
	v_pk_mov_b32 v[20:21], v[2:3], v[2:3]
	v_pk_mov_b32 v[22:23], v[2:3], v[2:3]
	v_pk_mov_b32 v[24:25], v[2:3], v[2:3]
	v_pk_mov_b32 v[34:35], v[2:3], v[2:3]
	v_pk_mov_b32 v[36:37], v[2:3], v[2:3]
	v_pk_mov_b32 v[38:39], v[2:3], v[2:3]
	v_pk_mov_b32 v[40:41], v[2:3], v[2:3]
	v_pk_mov_b32 v[50:51], v[2:3], v[2:3]
	v_pk_mov_b32 v[52:53], v[2:3], v[2:3]
	v_pk_mov_b32 v[54:55], v[2:3], v[2:3]
	v_pk_mov_b32 v[56:57], v[2:3], v[2:3]
	v_pk_mov_b32 v[10:11], v[2:3], v[2:3]
	v_pk_mov_b32 v[12:13], v[2:3], v[2:3]
	v_pk_mov_b32 v[14:15], v[2:3], v[2:3]
	v_pk_mov_b32 v[16:17], v[2:3], v[2:3]
	v_pk_mov_b32 v[26:27], v[2:3], v[2:3]
	v_pk_mov_b32 v[28:29], v[2:3], v[2:3]
	v_pk_mov_b32 v[30:31], v[2:3], v[2:3]
	v_pk_mov_b32 v[32:33], v[2:3], v[2:3]
	v_pk_mov_b32 v[42:43], v[2:3], v[2:3]
	v_pk_mov_b32 v[44:45], v[2:3], v[2:3]
	v_pk_mov_b32 v[46:47], v[2:3], v[2:3]
	v_pk_mov_b32 v[48:49], v[2:3], v[2:3]
	v_pk_mov_b32 v[58:59], v[2:3], v[2:3]
	v_pk_mov_b32 v[60:61], v[2:3], v[2:3]
	v_pk_mov_b32 v[62:63], v[2:3], v[2:3]
	v_pk_mov_b32 v[64:65], v[2:3], v[2:3]
	v_pk_mov_b32 v[66:67], v[2:3], v[2:3]
	v_pk_mov_b32 v[68:69], v[2:3], v[2:3]
	v_pk_mov_b32 v[70:71], v[2:3], v[2:3]
	v_pk_mov_b32 v[72:73], v[2:3], v[2:3]
	v_pk_mov_b32 v[82:83], v[2:3], v[2:3]
	v_pk_mov_b32 v[84:85], v[2:3], v[2:3]
	v_pk_mov_b32 v[86:87], v[2:3], v[2:3]
	v_pk_mov_b32 v[88:89], v[2:3], v[2:3]
	v_pk_mov_b32 v[98:99], v[2:3], v[2:3]
	v_pk_mov_b32 v[100:101], v[2:3], v[2:3]
	v_pk_mov_b32 v[102:103], v[2:3], v[2:3]
	v_pk_mov_b32 v[104:105], v[2:3], v[2:3]
	v_pk_mov_b32 v[118:119], v[2:3], v[2:3]
	v_pk_mov_b32 v[120:121], v[2:3], v[2:3]
	v_pk_mov_b32 v[122:123], v[2:3], v[2:3]
	v_pk_mov_b32 v[124:125], v[2:3], v[2:3]
	v_pk_mov_b32 v[74:75], v[2:3], v[2:3]
	v_pk_mov_b32 v[76:77], v[2:3], v[2:3]
	v_pk_mov_b32 v[78:79], v[2:3], v[2:3]
	v_pk_mov_b32 v[80:81], v[2:3], v[2:3]
	v_pk_mov_b32 v[90:91], v[2:3], v[2:3]
	v_pk_mov_b32 v[92:93], v[2:3], v[2:3]
	v_pk_mov_b32 v[94:95], v[2:3], v[2:3]
	v_pk_mov_b32 v[96:97], v[2:3], v[2:3]
	v_pk_mov_b32 v[106:107], v[2:3], v[2:3]
	v_pk_mov_b32 v[108:109], v[2:3], v[2:3]
	v_pk_mov_b32 v[110:111], v[2:3], v[2:3]
	v_pk_mov_b32 v[112:113], v[2:3], v[2:3]
	v_pk_mov_b32 v[130:131], v[2:3], v[2:3]
	v_pk_mov_b32 v[132:133], v[2:3], v[2:3]
	v_pk_mov_b32 v[134:135], v[2:3], v[2:3]
	v_pk_mov_b32 v[136:137], v[2:3], v[2:3]

;     __host__ __device__ bool next(int i, Unit& u) const { const int P = (i >> 1) * G + c; if (P >= 256) return false; u.pm = P >> 3; u.pn = (P & 7) + 8 * (i & 1); return true; }
; template <class Epi, class Sched, bool ALIGN_EPI = false, bool SP2 = false>
; __device__ __forceinline__ void gemm_phase(PG8_LAS unsigned char* lds, const Gemm g, const Sched& S, const Epi& E, const int wv) {
;     ...
;         const bool has_next = S.next(ui + 1, nxt);
;         const char* nA = has_next ? (const char*)g.A + (size_t)nxt.pm * tstepA + (g.amod ? (size_t)(nxt.pn % g.amod) * K * 2 : (size_t)0) : cA; const char* nB = has_next ? (const char*)g.Bt + (size_t)nxt.pn * tstepB : cB;
;         for (int t = 0; t < nt; t += 2) {
;             const bool last = (t == nt - 2);
;             const char* a1 = cA + (size_t)(t + 1) * kstep;
;             const char* a2 = last ? nA : cA + (size_t)(t + 2) * kstep; const char* b2 = last ? nB : cB + (size_t)(t + 2) * kstep;
;             const char* a3 = a2 + kstep; const char* b3 = b2 + kstep;
;     ...
; #pragma unroll
;         for (int a = 0; a < 2; ++a)
; #pragma unroll
;             for (int b = 0; b < 2; ++b)
; #pragma unroll
;                 for (int m = 0; m < 4; ++m)
; #pragma unroll
;                     for (int n = 0; n < 2; ++n) acc[a][b][m][n] = (f32x4){0.f, 0.f, 0.f, 0.f};
;         cur = nxt; cA = nA; cB = nB; ++ui;
.LBB0_1072:
	s_ashr_i32 s17, s16, 31
	s_lshl_b64 s[24:25], s[16:17], 20
	s_add_u32 s24, s43, s24
	v_mov_b32_e32 v133, 0
	s_addc_u32 s25, s44, s25
	s_andn2_b64 vcc, exec, s[12:13]
	v_mov_b32_e32 v132, v133
	v_pk_mov_b32 v[130:131], v[132:133], v[132:133]
	v_pk_mov_b32 v[128:129], v[132:133], v[132:133]
	v_pk_mov_b32 v[126:127], v[132:133], v[132:133]
	v_pk_mov_b32 v[116:117], v[132:133], v[132:133]
	v_pk_mov_b32 v[114:115], v[132:133], v[132:133]
	v_pk_mov_b32 v[112:113], v[132:133], v[132:133]
	v_pk_mov_b32 v[110:111], v[132:133], v[132:133]
	v_pk_mov_b32 v[100:101], v[132:133], v[132:133]
	v_pk_mov_b32 v[98:99], v[132:133], v[132:133]
	s_nop 0
	v_pk_mov_b32 v[96:97], v[132:133], v[132:133]
	v_pk_mov_b32 v[94:95], v[132:133], v[132:133]
	v_pk_mov_b32 v[84:85], v[132:133], v[132:133]
	v_pk_mov_b32 v[82:83], v[132:133], v[132:133]
	v_pk_mov_b32 v[80:81], v[132:133], v[132:133]
	v_pk_mov_b32 v[78:79], v[132:133], v[132:133]
	v_pk_mov_b32 v[124:125], v[132:133], v[132:133]
	v_pk_mov_b32 v[122:123], v[132:133], v[132:133]
	v_pk_mov_b32 v[120:121], v[132:133], v[132:133]
	v_pk_mov_b32 v[118:119], v[132:133], v[132:133]
	v_pk_mov_b32 v[108:109], v[132:133], v[132:133]
	v_pk_mov_b32 v[106:107], v[132:133], v[132:133]
	v_pk_mov_b32 v[104:105], v[132:133], v[132:133]
	v_pk_mov_b32 v[102:103], v[132:133], v[132:133]
	v_pk_mov_b32 v[92:93], v[132:133], v[132:133]
	v_pk_mov_b32 v[90:91], v[132:133], v[132:133]
	v_pk_mov_b32 v[88:89], v[132:133], v[132:133]
	v_pk_mov_b32 v[86:87], v[132:133], v[132:133]
	v_pk_mov_b32 v[76:77], v[132:133], v[132:133]
	v_pk_mov_b32 v[74:75], v[132:133], v[132:133]
	v_pk_mov_b32 v[72:73], v[132:133], v[132:133]
	v_pk_mov_b32 v[70:71], v[132:133], v[132:133]
	v_pk_mov_b32 v[68:69], v[132:133], v[132:133]
	v_pk_mov_b32 v[66:67], v[132:133], v[132:133]
	v_pk_mov_b32 v[64:65], v[132:133], v[132:133]
	v_pk_mov_b32 v[62:63], v[132:133], v[132:133]
	v_pk_mov_b32 v[52:53], v[132:133], v[132:133]
	v_pk_mov_b32 v[50:51], v[132:133], v[132:133]
	v_pk_mov_b32 v[48:49], v[132:133], v[132:133]
	v_pk_mov_b32 v[46:47], v[132:133], v[132:133]
	v_pk_mov_b32 v[36:37], v[132:133], v[132:133]
	v_pk_mov_b32 v[34:35], v[132:133], v[132:133]
	v_pk_mov_b32 v[32:33], v[132:133], v[132:133]
	v_pk_mov_b32 v[30:31], v[132:133], v[132:133]
	v_pk_mov_b32 v[20:21], v[132:133], v[132:133]
	v_pk_mov_b32 v[18:19], v[132:133], v[132:133]
	v_pk_mov_b32 v[16:17], v[132:133], v[132:133]
	v_pk_mov_b32 v[14:15], v[132:133], v[132:133]
	v_pk_mov_b32 v[60:61], v[132:133], v[132:133]
	v_pk_mov_b32 v[58:59], v[132:133], v[132:133]
	v_pk_mov_b32 v[56:57], v[132:133], v[132:133]
	v_pk_mov_b32 v[54:55], v[132:133], v[132:133]
	v_pk_mov_b32 v[44:45], v[132:133], v[132:133]
	v_pk_mov_b32 v[42:43], v[132:133], v[132:133]
	v_pk_mov_b32 v[40:41], v[132:133], v[132:133]
	v_pk_mov_b32 v[38:39], v[132:133], v[132:133]
	v_pk_mov_b32 v[28:29], v[132:133], v[132:133]
	v_pk_mov_b32 v[26:27], v[132:133], v[132:133]
	v_pk_mov_b32 v[24:25], v[132:133], v[132:133]
	v_pk_mov_b32 v[22:23], v[132:133], v[132:133]
	v_pk_mov_b32 v[12:13], v[132:133], v[132:133]
	v_pk_mov_b32 v[10:11], v[132:133], v[132:133]
	v_pk_mov_b32 v[8:9], v[132:133], v[132:133]
	v_pk_mov_b32 v[6:7], v[132:133], v[132:133]
	s_cbranch_vccnz .LBB0_1076
	s_and_b64 s[40:41], s[40:41], exec
	s_cselect_b32 s17, s25, s29
	s_cselect_b32 s40, s24, s28
	s_add_u32 s28, s28, 0x80080
	s_addc_u32 s29, s29, 0
	s_add_u32 s41, s30, 0x100
	v_mov_b32_e32 v6, 0
	s_addc_u32 s62, s31, 0
	s_mov_b32 s30, 0
	v_mov_b32_e32 v7, v6
	v_pk_mov_b32 v[8:9], v[6:7], v[6:7]
	v_pk_mov_b32 v[10:11], v[6:7], v[6:7]
	v_pk_mov_b32 v[12:13], v[6:7], v[6:7]
	v_pk_mov_b32 v[22:23], v[6:7], v[6:7]
	v_pk_mov_b32 v[24:25], v[6:7], v[6:7]
	v_pk_mov_b32 v[26:27], v[6:7], v[6:7]
	v_pk_mov_b32 v[28:29], v[6:7], v[6:7]
	v_pk_mov_b32 v[38:39], v[6:7], v[6:7]
	v_pk_mov_b32 v[40:41], v[6:7], v[6:7]
	v_pk_mov_b32 v[42:43], v[6:7], v[6:7]
	v_pk_mov_b32 v[44:45], v[6:7], v[6:7]
	v_pk_mov_b32 v[54:55], v[6:7], v[6:7]
	v_pk_mov_b32 v[56:57], v[6:7], v[6:7]
	v_pk_mov_b32 v[58:59], v[6:7], v[6:7]
	v_pk_mov_b32 v[60:61], v[6:7], v[6:7]
	v_pk_mov_b32 v[14:15], v[6:7], v[6:7]
	v_pk_mov_b32 v[16:17], v[6:7], v[6:7]
	v_pk_mov_b32 v[18:19], v[6:7], v[6:7]
	v_pk_mov_b32 v[20:21], v[6:7], v[6:7]
	v_pk_mov_b32 v[30:31], v[6:7], v[6:7]
	v_pk_mov_b32 v[32:33], v[6:7], v[6:7]
	v_pk_mov_b32 v[34:35], v[6:7], v[6:7]
	v_pk_mov_b32 v[36:37], v[6:7], v[6:7]
	v_pk_mov_b32 v[46:47], v[6:7], v[6:7]
	v_pk_mov_b32 v[48:49], v[6:7], v[6:7]
	v_pk_mov_b32 v[50:51], v[6:7], v[6:7]
	v_pk_mov_b32 v[52:53], v[6:7], v[6:7]
	v_pk_mov_b32 v[62:63], v[6:7], v[6:7]
	v_pk_mov_b32 v[64:65], v[6:7], v[6:7]
	v_pk_mov_b32 v[66:67], v[6:7], v[6:7]
	v_pk_mov_b32 v[68:69], v[6:7], v[6:7]
	v_pk_mov_b32 v[70:71], v[6:7], v[6:7]
	v_pk_mov_b32 v[72:73], v[6:7], v[6:7]
	v_pk_mov_b32 v[74:75], v[6:7], v[6:7]
	v_pk_mov_b32 v[76:77], v[6:7], v[6:7]
	v_pk_mov_b32 v[86:87], v[6:7], v[6:7]
	v_pk_mov_b32 v[88:89], v[6:7], v[6:7]
	v_pk_mov_b32 v[90:91], v[6:7], v[6:7]
	v_pk_mov_b32 v[92:93], v[6:7], v[6:7]
	v_pk_mov_b32 v[102:103], v[6:7], v[6:7]
	v_pk_mov_b32 v[104:105], v[6:7], v[6:7]
	v_pk_mov_b32 v[106:107], v[6:7], v[6:7]
	v_pk_mov_b32 v[108:109], v[6:7], v[6:7]
	v_pk_mov_b32 v[118:119], v[6:7], v[6:7]
	v_pk_mov_b32 v[120:121], v[6:7], v[6:7]
	v_pk_mov_b32 v[122:123], v[6:7], v[6:7]
	v_pk_mov_b32 v[124:125], v[6:7], v[6:7]
	v_pk_mov_b32 v[78:79], v[6:7], v[6:7]
	v_pk_mov_b32 v[80:81], v[6:7], v[6:7]
	v_pk_mov_b32 v[82:83], v[6:7], v[6:7]
	v_pk_mov_b32 v[84:85], v[6:7], v[6:7]
	v_pk_mov_b32 v[94:95], v[6:7], v[6:7]
	v_pk_mov_b32 v[96:97], v[6:7], v[6:7]
	v_pk_mov_b32 v[98:99], v[6:7], v[6:7]
	v_pk_mov_b32 v[100:101], v[6:7], v[6:7]
	v_pk_mov_b32 v[110:111], v[6:7], v[6:7]
	v_pk_mov_b32 v[112:113], v[6:7], v[6:7]
	v_pk_mov_b32 v[114:115], v[6:7], v[6:7]
	v_pk_mov_b32 v[116:117], v[6:7], v[6:7]
	v_pk_mov_b32 v[126:127], v[6:7], v[6:7]
	v_pk_mov_b32 v[128:129], v[6:7], v[6:7]
	v_pk_mov_b32 v[130:131], v[6:7], v[6:7]
	v_pk_mov_b32 v[132:133], v[6:7], v[6:7]

; template <class Epi, class Sched, bool ALIGN_EPI = false, bool SP2 = false>
; __device__ __forceinline__ void gemm_phase(PG8_LAS unsigned char* lds, const Gemm g, const Sched& S, const Epi& E, const int wv) {
;     ...
; #pragma unroll
;         for (int a = 0; a < 2; ++a)
; #pragma unroll
;             for (int b = 0; b < 2; ++b)
; #pragma unroll
;                 for (int m = 0; m < 4; ++m)
; #pragma unroll
;                     for (int n = 0; n < 2; ++n) acc[a][b][m][n] = (f32x4){0.f, 0.f, 0.f, 0.f};
;         cur = nxt; cA = nA; cB = nB; ++ui;
.LBB0_1359:
	s_ashr_i32 s13, s12, 31
	s_lshl_b64 s[48:49], s[12:13], 19
	s_add_u32 s48, s17, s48
	v_mov_b32_e32 v137, 0
	s_addc_u32 s49, s58, s49
	s_andn2_b64 vcc, exec, s[10:11]
	v_mov_b32_e32 v136, v137
	v_pk_mov_b32 v[134:135], v[136:137], v[136:137]
	v_pk_mov_b32 v[132:133], v[136:137], v[136:137]
	v_pk_mov_b32 v[130:131], v[136:137], v[136:137]
	v_pk_mov_b32 v[112:113], v[136:137], v[136:137]
	v_pk_mov_b32 v[110:111], v[136:137], v[136:137]
	v_pk_mov_b32 v[108:109], v[136:137], v[136:137]
	v_pk_mov_b32 v[106:107], v[136:137], v[136:137]
	v_pk_mov_b32 v[96:97], v[136:137], v[136:137]
	v_pk_mov_b32 v[94:95], v[136:137], v[136:137]
	v_pk_mov_b32 v[92:93], v[136:137], v[136:137]
	v_pk_mov_b32 v[90:91], v[136:137], v[136:137]
	v_pk_mov_b32 v[80:81], v[136:137], v[136:137]
	v_pk_mov_b32 v[78:79], v[136:137], v[136:137]
	v_pk_mov_b32 v[76:77], v[136:137], v[136:137]
	v_pk_mov_b32 v[74:75], v[136:137], v[136:137]
	v_pk_mov_b32 v[124:125], v[136:137], v[136:137]
	v_pk_mov_b32 v[122:123], v[136:137], v[136:137]
	v_pk_mov_b32 v[120:121], v[136:137], v[136:137]
	v_pk_mov_b32 v[118:119], v[136:137], v[136:137]
	v_pk_mov_b32 v[104:105], v[136:137], v[136:137]
	v_pk_mov_b32 v[102:103], v[136:137], v[136:137]
	v_pk_mov_b32 v[100:101], v[136:137], v[136:137]
	v_pk_mov_b32 v[98:99], v[136:137], v[136:137]
	v_pk_mov_b32 v[88:89], v[136:137], v[136:137]
	v_pk_mov_b32 v[86:87], v[136:137], v[136:137]
	v_pk_mov_b32 v[84:85], v[136:137], v[136:137]
	v_pk_mov_b32 v[82:83], v[136:137], v[136:137]
	v_pk_mov_b32 v[72:73], v[136:137], v[136:137]
	v_pk_mov_b32 v[70:71], v[136:137], v[136:137]
	v_pk_mov_b32 v[68:69], v[136:137], v[136:137]
	v_pk_mov_b32 v[66:67], v[136:137], v[136:137]
	v_pk_mov_b32 v[64:65], v[136:137], v[136:137]
	v_pk_mov_b32 v[62:63], v[136:137], v[136:137]
	v_pk_mov_b32 v[60:61], v[136:137], v[136:137]
	v_pk_mov_b32 v[58:59], v[136:137], v[136:137]
	v_pk_mov_b32 v[48:49], v[136:137], v[136:137]
	v_pk_mov_b32 v[46:47], v[136:137], v[136:137]
	v_pk_mov_b32 v[44:45], v[136:137], v[136:137]
	v_pk_mov_b32 v[42:43], v[136:137], v[136:137]
	v_pk_mov_b32 v[32:33], v[136:137], v[136:137]
	v_pk_mov_b32 v[30:31], v[136:137], v[136:137]
	v_pk_mov_b32 v[28:29], v[136:137], v[136:137]
	v_pk_mov_b32 v[26:27], v[136:137], v[136:137]
	v_pk_mov_b32 v[16:17], v[136:137], v[136:137]
	v_pk_mov_b32 v[14:15], v[136:137], v[136:137]
	v_pk_mov_b32 v[12:13], v[136:137], v[136:137]
	v_pk_mov_b32 v[10:11], v[136:137], v[136:137]
	v_pk_mov_b32 v[56:57], v[136:137], v[136:137]
	v_pk_mov_b32 v[54:55], v[136:137], v[136:137]
	v_pk_mov_b32 v[52:53], v[136:137], v[136:137]
	v_pk_mov_b32 v[50:51], v[136:137], v[136:137]
	v_pk_mov_b32 v[40:41], v[136:137], v[136:137]
	v_pk_mov_b32 v[38:39], v[136:137], v[136:137]
	v_pk_mov_b32 v[36:37], v[136:137], v[136:137]
	v_pk_mov_b32 v[34:35], v[136:137], v[136:137]
	v_pk_mov_b32 v[24:25], v[136:137], v[136:137]
	v_pk_mov_b32 v[22:23], v[136:137], v[136:137]
	v_pk_mov_b32 v[20:21], v[136:137], v[136:137]
	v_pk_mov_b32 v[18:19], v[136:137], v[136:137]
	v_pk_mov_b32 v[8:9], v[136:137], v[136:137]
	v_pk_mov_b32 v[6:7], v[136:137], v[136:137]
	v_pk_mov_b32 v[4:5], v[136:137], v[136:137]
	v_pk_mov_b32 v[2:3], v[136:137], v[136:137]
	s_cbranch_vccz .LBB0_1384
	s_and_b64 vcc, exec, s[46:47]
	s_cbranch_vccnz .LBB0_1387

;     __host__ __device__ bool next(int i, Unit& u) const { const int P = (i >> 1) * G + c; if (P >= 256) return false; u.pm = P >> 3; u.pn = (P & 7) + 8 * (i & 1); return true; }
; template <class Epi, class Sched, bool ALIGN_EPI = false, bool SP2 = false>
; __device__ __forceinline__ void gemm_phase(PG8_LAS unsigned char* lds, const Gemm g, const Sched& S, const Epi& E, const int wv) {
;     ...
;         const bool has_next = S.next(ui + 1, nxt);
;         const char* nA = has_next ? (const char*)g.A + (size_t)nxt.pm * tstepA + (g.amod ? (size_t)(nxt.pn % g.amod) * K * 2 : (size_t)0) : cA; const char* nB = has_next ? (const char*)g.Bt + (size_t)nxt.pn * tstepB : cB;
;         for (int t = 0; t < nt; t += 2) {
;             const bool last = (t == nt - 2);
;             const char* a1 = cA + (size_t)(t + 1) * kstep;
;             const char* a2 = last ? nA : cA + (size_t)(t + 2) * kstep; const char* b2 = last ? nB : cB + (size_t)(t + 2) * kstep;
;             const char* a3 = a2 + kstep; const char* b3 = b2 + kstep;
;     ...
; #pragma unroll
;         for (int a = 0; a < 2; ++a)
; #pragma unroll
;             for (int b = 0; b < 2; ++b)
; #pragma unroll
;                 for (int m = 0; m < 4; ++m)
; #pragma unroll
;                     for (int n = 0; n < 2; ++n) acc[a][b][m][n] = (f32x4){0.f, 0.f, 0.f, 0.f};
;         cur = nxt; cA = nA; cB = nB; ++ui;
.LBB0_1384:
	s_and_b64 s[44:45], s[44:45], exec
	s_cselect_b32 s13, s49, s53
	s_cselect_b32 s19, s48, s52
	s_add_u32 s44, s52, 0x40080
	s_addc_u32 s45, s53, 0
	s_add_u32 s54, s54, 0x100
	v_mov_b32_e32 v2, 0
	s_addc_u32 s55, s55, 0
	s_mov_b32 s52, 0
	v_mov_b32_e32 v3, v2
	v_pk_mov_b32 v[4:5], v[2:3], v[2:3]
	v_pk_mov_b32 v[6:7], v[2:3], v[2:3]
	v_pk_mov_b32 v[8:9], v[2:3], v[2:3]
	v_pk_mov_b32 v[18:19], v[2:3], v[2:3]
	v_pk_mov_b32 v[20:21], v[2:3], v[2:3]
	v_pk_mov_b32 v[22:23], v[2:3], v[2:3]
	v_pk_mov_b32 v[24:25], v[2:3], v[2:3]
	v_pk_mov_b32 v[34:35], v[2:3], v[2:3]
	v_pk_mov_b32 v[36:37], v[2:3], v[2:3]
	v_pk_mov_b32 v[38:39], v[2:3], v[2:3]
	v_pk_mov_b32 v[40:41], v[2:3], v[2:3]
	v_pk_mov_b32 v[50:51], v[2:3], v[2:3]
	v_pk_mov_b32 v[52:53], v[2:3], v[2:3]
	v_pk_mov_b32 v[54:55], v[2:3], v[2:3]
	v_pk_mov_b32 v[56:57], v[2:3], v[2:3]
	v_pk_mov_b32 v[10:11], v[2:3], v[2:3]
	v_pk_mov_b32 v[12:13], v[2:3], v[2:3]
	v_pk_mov_b32 v[14:15], v[2:3], v[2:3]
	v_pk_mov_b32 v[16:17], v[2:3], v[2:3]
	v_pk_mov_b32 v[26:27], v[2:3], v[2:3]
	v_pk_mov_b32 v[28:29], v[2:3], v[2:3]
	v_pk_mov_b32 v[30:31], v[2:3], v[2:3]
	v_pk_mov_b32 v[32:33], v[2:3], v[2:3]
	v_pk_mov_b32 v[42:43], v[2:3], v[2:3]
	v_pk_mov_b32 v[44:45], v[2:3], v[2:3]
	v_pk_mov_b32 v[46:47], v[2:3], v[2:3]
	v_pk_mov_b32 v[48:49], v[2:3], v[2:3]
	v_pk_mov_b32 v[58:59], v[2:3], v[2:3]
	v_pk_mov_b32 v[60:61], v[2:3], v[2:3]
	v_pk_mov_b32 v[62:63], v[2:3], v[2:3]
	v_pk_mov_b32 v[64:65], v[2:3], v[2:3]
	v_pk_mov_b32 v[66:67], v[2:3], v[2:3]
	v_pk_mov_b32 v[68:69], v[2:3], v[2:3]
	v_pk_mov_b32 v[70:71], v[2:3], v[2:3]
	v_pk_mov_b32 v[72:73], v[2:3], v[2:3]
	v_pk_mov_b32 v[82:83], v[2:3], v[2:3]
	v_pk_mov_b32 v[84:85], v[2:3], v[2:3]
	v_pk_mov_b32 v[86:87], v[2:3], v[2:3]
	v_pk_mov_b32 v[88:89], v[2:3], v[2:3]
	v_pk_mov_b32 v[98:99], v[2:3], v[2:3]
	v_pk_mov_b32 v[100:101], v[2:3], v[2:3]
	v_pk_mov_b32 v[102:103], v[2:3], v[2:3]
	v_pk_mov_b32 v[104:105], v[2:3], v[2:3]
	v_pk_mov_b32 v[118:119], v[2:3], v[2:3]
	v_pk_mov_b32 v[120:121], v[2:3], v[2:3]
	v_pk_mov_b32 v[122:123], v[2:3], v[2:3]
	v_pk_mov_b32 v[124:125], v[2:3], v[2:3]
	v_pk_mov_b32 v[74:75], v[2:3], v[2:3]
	v_pk_mov_b32 v[76:77], v[2:3], v[2:3]
	v_pk_mov_b32 v[78:79], v[2:3], v[2:3]
	v_pk_mov_b32 v[80:81], v[2:3], v[2:3]
	v_pk_mov_b32 v[90:91], v[2:3], v[2:3]
	v_pk_mov_b32 v[92:93], v[2:3], v[2:3]
	v_pk_mov_b32 v[94:95], v[2:3], v[2:3]
	v_pk_mov_b32 v[96:97], v[2:3], v[2:3]
	v_pk_mov_b32 v[106:107], v[2:3], v[2:3]
	v_pk_mov_b32 v[108:109], v[2:3], v[2:3]
	v_pk_mov_b32 v[110:111], v[2:3], v[2:3]
	v_pk_mov_b32 v[112:113], v[2:3], v[2:3]
	v_pk_mov_b32 v[130:131], v[2:3], v[2:3]
	v_pk_mov_b32 v[132:133], v[2:3], v[2:3]
	v_pk_mov_b32 v[134:135], v[2:3], v[2:3]
	v_pk_mov_b32 v[136:137], v[2:3], v[2:3]

; template <class Epi, class Sched, bool ALIGN_EPI = false, bool SP2 = false>
; __device__ __forceinline__ void gemm_phase(PG8_LAS unsigned char* lds, const Gemm g, const Sched& S, const Epi& E, const int wv) {
;     ...
; #pragma unroll
;         for (int a = 0; a < 2; ++a)
; #pragma unroll
;             for (int b = 0; b < 2; ++b)
; #pragma unroll
;                 for (int m = 0; m < 4; ++m)
; #pragma unroll
;                     for (int n = 0; n < 2; ++n) acc[a][b][m][n] = (f32x4){0.f, 0.f, 0.f, 0.f};
;         cur = nxt; cA = nA; cB = nB; ++ui;
.LBB0_1468:
	s_ashr_i32 s51, s50, 31
	s_lshl_b64 s[14:15], s[50:51], 20
	s_add_u32 s90, s60, s14
	v_mov_b32_e32 v121, 0
	s_addc_u32 s91, s61, s15
	s_andn2_b64 vcc, exec, s[28:29]
	v_mov_b32_e32 v120, v121
	v_pk_mov_b32 v[118:119], v[120:121], v[120:121]
	v_pk_mov_b32 v[48:49], v[120:121], v[120:121]
	v_pk_mov_b32 v[46:47], v[120:121], v[120:121]
	v_pk_mov_b32 v[112:113], v[120:121], v[120:121]
	v_pk_mov_b32 v[110:111], v[120:121], v[120:121]
	v_pk_mov_b32 v[40:41], v[120:121], v[120:121]
	v_pk_mov_b32 v[38:39], v[120:121], v[120:121]
	v_pk_mov_b32 v[136:137], v[120:121], v[120:121]
	v_pk_mov_b32 v[134:135], v[120:121], v[120:121]
	v_pk_mov_b32 v[64:65], v[120:121], v[120:121]
	v_pk_mov_b32 v[62:63], v[120:121], v[120:121]
	v_pk_mov_b32 v[132:133], v[120:121], v[120:121]
	v_pk_mov_b32 v[130:131], v[120:121], v[120:121]
	v_pk_mov_b32 v[60:61], v[120:121], v[120:121]
	v_pk_mov_b32 v[58:59], v[120:121], v[120:121]
	v_pk_mov_b32 v[116:117], v[120:121], v[120:121]
	v_pk_mov_b32 v[114:115], v[120:121], v[120:121]
	v_pk_mov_b32 v[44:45], v[120:121], v[120:121]
	v_pk_mov_b32 v[42:43], v[120:121], v[120:121]
	v_pk_mov_b32 v[108:109], v[120:121], v[120:121]
	v_pk_mov_b32 v[106:107], v[120:121], v[120:121]
	v_pk_mov_b32 v[36:37], v[120:121], v[120:121]
	v_pk_mov_b32 v[34:35], v[120:121], v[120:121]
	v_pk_mov_b32 v[128:129], v[120:121], v[120:121]
	v_pk_mov_b32 v[126:127], v[120:121], v[120:121]
	v_pk_mov_b32 v[56:57], v[120:121], v[120:121]
	v_pk_mov_b32 v[54:55], v[120:121], v[120:121]
	v_pk_mov_b32 v[124:125], v[120:121], v[120:121]
	v_pk_mov_b32 v[122:123], v[120:121], v[120:121]
	v_pk_mov_b32 v[52:53], v[120:121], v[120:121]
	v_pk_mov_b32 v[50:51], v[120:121], v[120:121]
	v_pk_mov_b32 v[88:89], v[120:121], v[120:121]
	v_pk_mov_b32 v[86:87], v[120:121], v[120:121]
	v_pk_mov_b32 v[16:17], v[120:121], v[120:121]
	v_pk_mov_b32 v[14:15], v[120:121], v[120:121]
	v_pk_mov_b32 v[72:73], v[120:121], v[120:121]
	v_pk_mov_b32 v[70:71], v[120:121], v[120:121]
	v_pk_mov_b32 v[8:9], v[120:121], v[120:121]
	v_pk_mov_b32 v[6:7], v[120:121], v[120:121]
	v_pk_mov_b32 v[104:105], v[120:121], v[120:121]
	v_pk_mov_b32 v[102:103], v[120:121], v[120:121]
	v_pk_mov_b32 v[32:33], v[120:121], v[120:121]
	v_pk_mov_b32 v[30:31], v[120:121], v[120:121]
	v_pk_mov_b32 v[100:101], v[120:121], v[120:121]
	v_pk_mov_b32 v[98:99], v[120:121], v[120:121]
	v_pk_mov_b32 v[28:29], v[120:121], v[120:121]
	v_pk_mov_b32 v[26:27], v[120:121], v[120:121]
	v_pk_mov_b32 v[84:85], v[120:121], v[120:121]
	v_pk_mov_b32 v[82:83], v[120:121], v[120:121]
	v_pk_mov_b32 v[12:13], v[120:121], v[120:121]
	v_pk_mov_b32 v[10:11], v[120:121], v[120:121]
	v_pk_mov_b32 v[68:69], v[120:121], v[120:121]
	v_pk_mov_b32 v[66:67], v[120:121], v[120:121]
	v_pk_mov_b32 v[4:5], v[120:121], v[120:121]
	v_pk_mov_b32 v[2:3], v[120:121], v[120:121]
	v_pk_mov_b32 v[96:97], v[120:121], v[120:121]
	v_pk_mov_b32 v[94:95], v[120:121], v[120:121]
	v_pk_mov_b32 v[24:25], v[120:121], v[120:121]
	v_pk_mov_b32 v[22:23], v[120:121], v[120:121]
	v_pk_mov_b32 v[92:93], v[120:121], v[120:121]
	v_pk_mov_b32 v[90:91], v[120:121], v[120:121]
	v_pk_mov_b32 v[20:21], v[120:121], v[120:121]
	v_pk_mov_b32 v[18:19], v[120:121], v[120:121]
	s_cbranch_vccz .LBB0_1494
	s_and_b64 vcc, exec, s[30:31]
	s_cbranch_vccnz .LBB0_1497
